# GEMM1 q/k tiles: the 8 norm-weight vectors loaded once per tile (was 4 serialized load->wait pairs per token block); next-tile prefetch dropped to free the registers
# speedup vs baseline: 1.0013x; 1.0013x over previous
.LBB0_231:
	s_andn2_saveexec_b64 s[38:39], s[38:39]
	s_cbranch_execz .LBB0_262
	v_mul_f32_e32 v105, v66, v66
	v_mul_f32_e32 v109, v67, v67
	v_fmac_f32_e32 v105, v82, v82
	v_fmac_f32_e32 v109, v83, v83
	v_add_f32_e32 v105, v105, v109
	v_mul_f32_e32 v109, v68, v68
	v_fmac_f32_e32 v109, v84, v84
	v_add_f32_e32 v105, v109, v105
	v_mul_f32_e32 v109, v69, v69
	v_fmac_f32_e32 v109, v85, v85
	v_add_f32_e32 v105, v109, v105
	v_mul_f32_e32 v109, v70, v70
	v_fmac_f32_e32 v109, v86, v86
	v_add_f32_e32 v105, v109, v105
	v_mul_f32_e32 v109, v71, v71
	v_fmac_f32_e32 v109, v87, v87
	v_pk_mul_f32 v[120:121], v[72:73], v[72:73]
	v_add_f32_e32 v105, v109, v105
	v_pk_fma_f32 v[120:121], v[88:89], v[88:89], v[120:121]
	v_pk_mul_f32 v[122:123], v[74:75], v[74:75]
	v_add_f32_e32 v105, v120, v105
	v_pk_fma_f32 v[122:123], v[90:91], v[90:91], v[122:123]
	v_add_f32_e32 v105, v121, v105
	v_pk_mul_f32 v[162:163], v[76:77], v[76:77]
	v_add_f32_e32 v105, v122, v105
	v_pk_fma_f32 v[162:163], v[92:93], v[92:93], v[162:163]
	v_add_f32_e32 v105, v123, v105
	v_pk_mul_f32 v[164:165], v[78:79], v[78:79]
	v_add_f32_e32 v105, v162, v105
	v_pk_fma_f32 v[164:165], v[94:95], v[94:95], v[164:165]
	v_add_f32_e32 v105, v163, v105
	v_and_b32_e32 v117, 64, v132
	v_pk_mul_f32 v[166:167], v[80:81], v[80:81]
	v_add_f32_e32 v105, v164, v105
	v_xor_b32_e32 v109, 32, v132
	v_add_u32_e32 v117, 64, v117
	v_pk_fma_f32 v[166:167], v[96:97], v[96:97], v[166:167]
	v_add_f32_e32 v105, v165, v105
	v_cmp_lt_i32_e64 s[14:15], v109, v117
	v_add_f32_e32 v105, v166, v105
	v_add_f32_e32 v105, v167, v105
	v_cndmask_b32_e64 v109, v132, v109, s[14:15]
	v_lshlrev_b32_e32 v109, 2, v109
	ds_bpermute_b32 v109, v109, v105
	v_permlane32_swap_b32_e32 v82, v66
	v_permlane32_swap_b32_e32 v83, v67
	v_permlane32_swap_b32_e32 v84, v68
	v_permlane32_swap_b32_e32 v85, v69
	v_permlane32_swap_b32_e32 v86, v70
	v_permlane32_swap_b32_e32 v87, v71
	v_permlane32_swap_b32_e32 v88, v72
	v_permlane32_swap_b32_e32 v89, v73
	v_permlane32_swap_b32_e32 v90, v74
	v_permlane32_swap_b32_e32 v91, v75
	v_permlane32_swap_b32_e32 v92, v76
	v_permlane32_swap_b32_e32 v93, v77
	v_permlane32_swap_b32_e32 v94, v78
	v_permlane32_swap_b32_e32 v95, v79
	v_permlane32_swap_b32_e32 v96, v80
	v_permlane32_swap_b32_e32 v97, v81
	v_ashrrev_i32_e32 v119, 31, v118
	s_and_saveexec_b64 s[14:15], s[6:7]
	s_xor_b64 s[14:15], exec, s[14:15]
	v_lshlrev_b64 v[118:119], 10, v[118:119]
	v_lshl_add_u64 v[122:123], v[110:111], 0, v[118:119]
	s_or_saveexec_b64 s[14:15], s[14:15]
	s_mov_b64 s[40:41], 0
	s_xor_b64 exec, exec, s[14:15]
	v_lshl_add_u64 v[118:119], v[106:107], 0, v[118:119]
	v_lshlrev_b64 v[118:119], 7, v[118:119]
	v_lshl_add_u64 v[122:123], s[22:23], 0, v[118:119]
	s_and_b64 s[40:41], s[12:13], exec
	s_or_b64 exec, exec, s[14:15]
	s_waitcnt lgkmcnt(0)
	v_add_f32_e32 v105, v105, v109
	v_fmamk_f32 v105, v105, 0x3c800000, v124
	v_cmp_gt_f32_e64 s[14:15], s58, v105
	v_mul_f32_e32 v109, 0x4b800000, v105
	v_readlane_b32 s76, v245, 16
	v_cndmask_b32_e64 v105, v105, v109, s[14:15]
	v_rsq_f32_e32 v105, v105
	v_readlane_b32 s77, v245, 17
	v_readlane_b32 s78, v245, 18
	v_readlane_b32 s79, v245, 19
	v_readlane_b32 s80, v245, 20
	v_readlane_b32 s81, v245, 21
	v_readlane_b32 s82, v245, 22
	v_readlane_b32 s83, v245, 23
	v_readlane_b32 s84, v245, 24
	v_readlane_b32 s85, v245, 25
	v_readlane_b32 s86, v245, 26
	v_readlane_b32 s87, v245, 27
	v_readlane_b32 s88, v245, 28
	v_readlane_b32 s89, v245, 29
	v_readlane_b32 s90, v245, 30
	v_readlane_b32 s91, v245, 31
	s_mov_b64 s[76:77], s[80:81]
	v_mul_f32_e32 v109, 0x45800000, v105
	s_mov_b64 s[78:79], s[82:83]
	s_mov_b64 s[80:81], s[84:85]
	s_mov_b64 s[82:83], s[86:87]
	s_mov_b64 s[84:85], s[88:89]
	s_mov_b64 s[86:87], s[90:91]
	v_cndmask_b32_e64 v118, v105, v109, s[14:15]
	v_mov_b32_e32 v105, s85
	v_mov_b32_e32 v109, s87
	v_cndmask_b32_e64 v121, v105, v109, s[4:5]
	v_mov_b32_e32 v105, s84
	v_mov_b32_e32 v109, s86
	v_cndmask_b32_e64 v120, v105, v109, s[4:5]
	v_lshlrev_b32_e32 v162, 2, v100
	v_mov_b32_e32 v163, v99
	v_lshl_add_u64 v[120:121], v[120:121], 0, v[162:163]
	global_load_dwordx4 v[246:249], v[120:121], off
	global_load_dwordx4 v[214:217], v[120:121], off offset:16
	global_load_dwordx4 v[218:221], v[120:121], off offset:32
	global_load_dwordx4 v[222:225], v[120:121], off offset:48
	global_load_dwordx4 v[226:229], v[120:121], off offset:64
	global_load_dwordx4 v[230:233], v[120:121], off offset:80
	global_load_dwordx4 v[234:237], v[120:121], off offset:96
	global_load_dwordx4 v[238:241], v[120:121], off offset:112
	v_pk_mul_f32 v[82:83], v[118:119], v[82:83] op_sel_hi:[0,1]
	v_pk_mul_f32 v[84:85], v[118:119], v[84:85] op_sel_hi:[0,1]
	v_pk_mul_f32 v[66:67], v[118:119], v[66:67] op_sel_hi:[0,1]
	v_pk_mul_f32 v[68:69], v[118:119], v[68:69] op_sel_hi:[0,1]
	s_waitcnt vmcnt(0)
	v_pk_mul_f32 v[66:67], v[66:67], v[214:215]
	v_pk_mul_f32 v[82:83], v[82:83], v[246:247]
	v_pk_mul_f32 v[84:85], v[84:85], v[248:249]
	v_pk_mul_f32 v[68:69], v[68:69], v[216:217]
	s_and_saveexec_b64 s[14:15], s[40:41]
	s_cbranch_execz .LBB0_238
	v_add_u32_e32 v105, v158, v157
	ds_write_b128 v105, v[82:85]
	ds_write_b128 v105, v[66:69] offset:16
.LBB0_238:
	s_or_b64 exec, exec, s[14:15]
	v_pk_mul_f32 v[82:83], v[104:105], v[82:83] op_sel_hi:[0,1]
	v_pk_mul_f32 v[84:85], v[104:105], v[84:85] op_sel_hi:[0,1]
	v_pk_mul_f32 v[66:67], v[104:105], v[66:67] op_sel_hi:[0,1]
	v_lshlrev_b32_e32 v162, 1, v100
	v_mov_b32_e32 v163, v99
	v_cvt_pk_bf16_f32 v82, v82, v83
	v_cvt_pk_bf16_f32 v83, v84, v85
	v_cvt_pk_bf16_f32 v84, v66, v67
	v_pk_mul_f32 v[66:67], v[104:105], v[68:69] op_sel_hi:[0,1]
	v_lshl_add_u64 v[122:123], v[122:123], 0, v[162:163]
	v_cvt_pk_bf16_f32 v85, v66, v67
	ds_write_b128 v202, v[82:85]
	s_nop 1
	v_mov_b32_e32 v119, v118
	v_pk_mul_f32 v[86:87], v[118:119], v[86:87]
	v_pk_mul_f32 v[88:89], v[118:119], v[88:89]
	v_pk_mul_f32 v[162:163], v[118:119], v[70:71]
	v_pk_mul_f32 v[164:165], v[118:119], v[72:73]
	v_pk_mul_f32 v[70:71], v[86:87], v[218:219]
	v_pk_mul_f32 v[72:73], v[88:89], v[220:221]
	v_pk_mul_f32 v[66:67], v[162:163], v[222:223]
	v_pk_mul_f32 v[68:69], v[164:165], v[224:225]
	s_and_saveexec_b64 s[14:15], s[40:41]
	s_cbranch_execz .LBB0_240
	v_add_u32_e32 v82, v158, v157
	ds_write_b128 v82, v[70:73] offset:32
	ds_write_b128 v82, v[66:69] offset:48
.LBB0_240:
	s_or_b64 exec, exec, s[14:15]
	v_mov_b32_e32 v105, v104
	v_pk_mul_f32 v[70:71], v[104:105], v[70:71]
	v_pk_mul_f32 v[72:73], v[104:105], v[72:73]
	v_pk_mul_f32 v[66:67], v[104:105], v[66:67]
	v_cvt_pk_bf16_f32 v70, v70, v71
	v_cvt_pk_bf16_f32 v71, v72, v73
	v_cvt_pk_bf16_f32 v72, v66, v67
	v_pk_mul_f32 v[66:67], v[104:105], v[68:69]
	v_pk_mul_f32 v[74:75], v[118:119], v[74:75]
	v_cvt_pk_bf16_f32 v73, v66, v67
	ds_write_b128 v202, v[70:73] offset:16
	s_nop 1
	v_pk_mul_f32 v[70:71], v[118:119], v[90:91]
	v_pk_mul_f32 v[72:73], v[118:119], v[92:93]
	v_pk_mul_f32 v[76:77], v[118:119], v[76:77]
	v_pk_mul_f32 v[70:71], v[70:71], v[226:227]
	v_pk_mul_f32 v[72:73], v[72:73], v[228:229]
	v_pk_mul_f32 v[66:67], v[74:75], v[230:231]
	v_pk_mul_f32 v[68:69], v[76:77], v[232:233]
	s_and_saveexec_b64 s[14:15], s[40:41]
	s_cbranch_execz .LBB0_242
	v_add_u32_e32 v74, v158, v157
	ds_write_b128 v74, v[70:73] offset:64
	ds_write_b128 v74, v[66:69] offset:80
.LBB0_242:
	s_or_b64 exec, exec, s[14:15]
	v_pk_mul_f32 v[70:71], v[104:105], v[70:71]
	v_pk_mul_f32 v[72:73], v[104:105], v[72:73]
	v_pk_mul_f32 v[66:67], v[104:105], v[66:67]
	v_cvt_pk_bf16_f32 v70, v70, v71
	v_cvt_pk_bf16_f32 v71, v72, v73
	v_cvt_pk_bf16_f32 v72, v66, v67
	v_pk_mul_f32 v[66:67], v[104:105], v[68:69]
	v_pk_mul_f32 v[78:79], v[118:119], v[78:79]
	v_cvt_pk_bf16_f32 v73, v66, v67
	ds_write_b128 v202, v[70:73] offset:32
	s_nop 1
	v_pk_mul_f32 v[70:71], v[118:119], v[94:95]
	v_pk_mul_f32 v[72:73], v[118:119], v[96:97]
	v_pk_mul_f32 v[80:81], v[118:119], v[80:81]
	v_pk_mul_f32 v[70:71], v[70:71], v[234:235]
	v_pk_mul_f32 v[72:73], v[72:73], v[236:237]
	v_pk_mul_f32 v[66:67], v[78:79], v[238:239]
	v_pk_mul_f32 v[68:69], v[80:81], v[240:241]
	s_and_saveexec_b64 s[14:15], s[40:41]
	s_cbranch_execz .LBB0_244
	v_add_u32_e32 v74, v158, v157
	ds_write_b128 v74, v[70:73] offset:96
	ds_write_b128 v74, v[66:69] offset:112

.LBB0_289:
	s_andn2_saveexec_b64 s[38:39], s[38:39]
	s_cbranch_execz .LBB0_320
	v_mul_f32_e32 v67, v34, v34
	v_mul_f32_e32 v69, v35, v35
	v_fmac_f32_e32 v67, v50, v50
	v_fmac_f32_e32 v69, v51, v51
	v_add_f32_e32 v67, v67, v69
	v_mul_f32_e32 v69, v36, v36
	v_fmac_f32_e32 v69, v52, v52
	v_add_f32_e32 v67, v69, v67
	v_mul_f32_e32 v69, v37, v37
	v_fmac_f32_e32 v69, v53, v53
	v_add_f32_e32 v67, v69, v67
	v_mul_f32_e32 v69, v38, v38
	v_fmac_f32_e32 v69, v54, v54
	v_add_f32_e32 v67, v69, v67
	v_mul_f32_e32 v69, v39, v39
	v_fmac_f32_e32 v69, v55, v55
	v_pk_mul_f32 v[70:71], v[40:41], v[40:41]
	v_add_f32_e32 v67, v69, v67
	v_pk_fma_f32 v[70:71], v[56:57], v[56:57], v[70:71]
	v_pk_mul_f32 v[72:73], v[42:43], v[42:43]
	v_add_f32_e32 v67, v70, v67
	v_pk_fma_f32 v[72:73], v[58:59], v[58:59], v[72:73]
	v_add_f32_e32 v67, v71, v67
	v_pk_mul_f32 v[74:75], v[44:45], v[44:45]
	v_add_f32_e32 v67, v72, v67
	v_pk_fma_f32 v[74:75], v[60:61], v[60:61], v[74:75]
	v_add_f32_e32 v67, v73, v67
	v_pk_mul_f32 v[76:77], v[46:47], v[46:47]
	v_add_f32_e32 v67, v74, v67
	v_pk_fma_f32 v[76:77], v[62:63], v[62:63], v[76:77]
	v_add_f32_e32 v67, v75, v67
	v_and_b32_e32 v70, 64, v132
	v_pk_mul_f32 v[78:79], v[48:49], v[48:49]
	v_add_f32_e32 v67, v76, v67
	v_xor_b32_e32 v69, 32, v132
	v_add_u32_e32 v70, 64, v70
	v_pk_fma_f32 v[78:79], v[64:65], v[64:65], v[78:79]
	v_add_f32_e32 v67, v77, v67
	v_cmp_lt_i32_e64 s[14:15], v69, v70
	v_add_f32_e32 v67, v78, v67
	v_add_f32_e32 v67, v79, v67
	v_cndmask_b32_e64 v69, v132, v69, s[14:15]
	v_lshlrev_b32_e32 v69, 2, v69
	ds_bpermute_b32 v70, v69, v67
	v_permlane32_swap_b32_e32 v50, v34
	v_permlane32_swap_b32_e32 v51, v35
	v_permlane32_swap_b32_e32 v52, v36
	v_permlane32_swap_b32_e32 v53, v37
	v_permlane32_swap_b32_e32 v54, v38
	v_permlane32_swap_b32_e32 v55, v39
	v_permlane32_swap_b32_e32 v56, v40
	v_permlane32_swap_b32_e32 v57, v41
	v_permlane32_swap_b32_e32 v58, v42
	v_permlane32_swap_b32_e32 v59, v43
	v_permlane32_swap_b32_e32 v60, v44
	v_permlane32_swap_b32_e32 v61, v45
	v_permlane32_swap_b32_e32 v62, v46
	v_permlane32_swap_b32_e32 v63, v47
	v_permlane32_swap_b32_e32 v64, v48
	v_permlane32_swap_b32_e32 v65, v49
	v_ashrrev_i32_e32 v69, 31, v68
	s_and_saveexec_b64 s[14:15], s[6:7]
	s_xor_b64 s[14:15], exec, s[14:15]
	v_lshlrev_b64 v[68:69], 10, v[68:69]
	v_lshl_add_u64 v[72:73], v[110:111], 0, v[68:69]
	s_or_saveexec_b64 s[14:15], s[14:15]
	s_mov_b64 s[40:41], 0
	s_xor_b64 exec, exec, s[14:15]
	v_lshl_add_u64 v[68:69], v[106:107], 0, v[68:69]
	v_lshlrev_b64 v[68:69], 7, v[68:69]
	v_lshl_add_u64 v[72:73], s[22:23], 0, v[68:69]
	s_and_b64 s[40:41], s[12:13], exec
	s_or_b64 exec, exec, s[14:15]
	s_waitcnt lgkmcnt(0)
	v_add_f32_e32 v67, v67, v70
	v_fmamk_f32 v67, v67, 0x3c800000, v124
	v_cmp_gt_f32_e64 s[14:15], s58, v67
	v_mul_f32_e32 v68, 0x4b800000, v67
	v_readlane_b32 s76, v245, 16
	v_cndmask_b32_e64 v67, v67, v68, s[14:15]
	v_rsq_f32_e32 v67, v67
	v_readlane_b32 s77, v245, 17
	v_readlane_b32 s78, v245, 18
	v_readlane_b32 s79, v245, 19
	v_readlane_b32 s80, v245, 20
	v_readlane_b32 s81, v245, 21
	v_readlane_b32 s82, v245, 22
	v_readlane_b32 s83, v245, 23
	v_readlane_b32 s84, v245, 24
	v_readlane_b32 s85, v245, 25
	v_readlane_b32 s86, v245, 26
	v_readlane_b32 s87, v245, 27
	v_readlane_b32 s88, v245, 28
	v_readlane_b32 s89, v245, 29
	v_readlane_b32 s90, v245, 30
	v_readlane_b32 s91, v245, 31
	s_mov_b64 s[76:77], s[80:81]
	v_mul_f32_e32 v68, 0x45800000, v67
	s_mov_b64 s[78:79], s[82:83]
	s_mov_b64 s[80:81], s[84:85]
	s_mov_b64 s[82:83], s[86:87]
	s_mov_b64 s[84:85], s[88:89]
	s_mov_b64 s[86:87], s[90:91]
	v_cndmask_b32_e64 v68, v67, v68, s[14:15]
	v_mov_b32_e32 v67, s85
	v_mov_b32_e32 v69, s87
	v_cndmask_b32_e64 v71, v67, v69, s[4:5]
	v_mov_b32_e32 v67, s84
	v_mov_b32_e32 v69, s86
	v_cndmask_b32_e64 v70, v67, v69, s[4:5]
	v_lshlrev_b32_e32 v74, 2, v100
	v_mov_b32_e32 v75, v99
	v_lshl_add_u64 v[70:71], v[70:71], 0, v[74:75]
	v_pk_mul_f32 v[50:51], v[68:69], v[50:51] op_sel_hi:[0,1]
	v_pk_mul_f32 v[52:53], v[68:69], v[52:53] op_sel_hi:[0,1]
	v_pk_mul_f32 v[34:35], v[68:69], v[34:35] op_sel_hi:[0,1]
	v_pk_mul_f32 v[36:37], v[68:69], v[36:37] op_sel_hi:[0,1]
	v_pk_mul_f32 v[34:35], v[34:35], v[214:215]
	v_pk_mul_f32 v[50:51], v[50:51], v[246:247]
	v_pk_mul_f32 v[52:53], v[52:53], v[248:249]
	v_pk_mul_f32 v[36:37], v[36:37], v[216:217]
	s_and_saveexec_b64 s[14:15], s[40:41]
	s_cbranch_execz .LBB0_296
	v_add_u32_e32 v67, v158, v157
	ds_write_b128 v67, v[50:53]
	ds_write_b128 v67, v[34:37] offset:16
.LBB0_296:
	s_or_b64 exec, exec, s[14:15]
	v_pk_mul_f32 v[50:51], v[104:105], v[50:51] op_sel_hi:[0,1]
	v_pk_mul_f32 v[52:53], v[104:105], v[52:53] op_sel_hi:[0,1]
	v_pk_mul_f32 v[34:35], v[104:105], v[34:35] op_sel_hi:[0,1]
	v_lshlrev_b32_e32 v74, 1, v100
	v_mov_b32_e32 v75, v99
	v_cvt_pk_bf16_f32 v50, v50, v51
	v_cvt_pk_bf16_f32 v51, v52, v53
	v_cvt_pk_bf16_f32 v52, v34, v35
	v_pk_mul_f32 v[34:35], v[104:105], v[36:37] op_sel_hi:[0,1]
	v_lshl_add_u64 v[72:73], v[72:73], 0, v[74:75]
	v_cvt_pk_bf16_f32 v53, v34, v35
	ds_write_b128 v202, v[50:53]
	s_nop 1
	v_mov_b32_e32 v69, v68
	v_pk_mul_f32 v[54:55], v[68:69], v[54:55]
	v_pk_mul_f32 v[56:57], v[68:69], v[56:57]
	v_pk_mul_f32 v[74:75], v[68:69], v[38:39]
	v_pk_mul_f32 v[76:77], v[68:69], v[40:41]
	v_pk_mul_f32 v[38:39], v[54:55], v[218:219]
	v_pk_mul_f32 v[40:41], v[56:57], v[220:221]
	v_pk_mul_f32 v[34:35], v[74:75], v[222:223]
	v_pk_mul_f32 v[36:37], v[76:77], v[224:225]
	s_and_saveexec_b64 s[14:15], s[40:41]
	s_cbranch_execz .LBB0_298
	v_add_u32_e32 v50, v158, v157
	ds_write_b128 v50, v[38:41] offset:32
	ds_write_b128 v50, v[34:37] offset:48
.LBB0_298:
	s_or_b64 exec, exec, s[14:15]
	v_mov_b32_e32 v105, v104
	v_pk_mul_f32 v[38:39], v[104:105], v[38:39]
	v_pk_mul_f32 v[40:41], v[104:105], v[40:41]
	v_pk_mul_f32 v[34:35], v[104:105], v[34:35]
	v_cvt_pk_bf16_f32 v38, v38, v39
	v_cvt_pk_bf16_f32 v39, v40, v41
	v_cvt_pk_bf16_f32 v40, v34, v35
	v_pk_mul_f32 v[34:35], v[104:105], v[36:37]
	v_pk_mul_f32 v[42:43], v[68:69], v[42:43]
	v_cvt_pk_bf16_f32 v41, v34, v35
	ds_write_b128 v202, v[38:41] offset:16
	s_nop 1
	v_pk_mul_f32 v[38:39], v[68:69], v[58:59]
	v_pk_mul_f32 v[40:41], v[68:69], v[60:61]
	v_pk_mul_f32 v[44:45], v[68:69], v[44:45]
	v_pk_mul_f32 v[38:39], v[38:39], v[226:227]
	v_pk_mul_f32 v[40:41], v[40:41], v[228:229]
	v_pk_mul_f32 v[34:35], v[42:43], v[230:231]
	v_pk_mul_f32 v[36:37], v[44:45], v[232:233]
	s_and_saveexec_b64 s[14:15], s[40:41]
	s_cbranch_execz .LBB0_300
	v_add_u32_e32 v42, v158, v157
	ds_write_b128 v42, v[38:41] offset:64
	ds_write_b128 v42, v[34:37] offset:80
.LBB0_300:
	s_or_b64 exec, exec, s[14:15]
	v_pk_mul_f32 v[38:39], v[104:105], v[38:39]
	v_pk_mul_f32 v[40:41], v[104:105], v[40:41]
	v_pk_mul_f32 v[34:35], v[104:105], v[34:35]
	v_cvt_pk_bf16_f32 v38, v38, v39
	v_cvt_pk_bf16_f32 v39, v40, v41
	v_cvt_pk_bf16_f32 v40, v34, v35
	v_pk_mul_f32 v[34:35], v[104:105], v[36:37]
	v_pk_mul_f32 v[46:47], v[68:69], v[46:47]
	v_cvt_pk_bf16_f32 v41, v34, v35
	ds_write_b128 v202, v[38:41] offset:32
	s_nop 1
	v_pk_mul_f32 v[38:39], v[68:69], v[62:63]
	v_pk_mul_f32 v[40:41], v[68:69], v[64:65]
	v_pk_mul_f32 v[48:49], v[68:69], v[48:49]
	v_pk_mul_f32 v[38:39], v[38:39], v[234:235]
	v_pk_mul_f32 v[40:41], v[40:41], v[236:237]
	v_pk_mul_f32 v[34:35], v[46:47], v[238:239]
	v_pk_mul_f32 v[36:37], v[48:49], v[240:241]
	s_and_saveexec_b64 s[14:15], s[40:41]
	s_cbranch_execz .LBB0_302
	v_add_u32_e32 v42, v158, v157
	ds_write_b128 v42, v[38:41] offset:96
	ds_write_b128 v42, v[34:37] offset:112

.LBB0_348:
	s_andn2_saveexec_b64 s[30:31], s[30:31]
	s_cbranch_execz .LBB0_379
	v_mul_f32_e32 v35, v18, v18
	v_mul_f32_e32 v37, v19, v19
	v_fmac_f32_e32 v35, v2, v2
	v_fmac_f32_e32 v37, v3, v3
	v_add_f32_e32 v35, v35, v37
	v_mul_f32_e32 v37, v20, v20
	v_fmac_f32_e32 v37, v4, v4
	v_add_f32_e32 v35, v37, v35
	v_mul_f32_e32 v37, v21, v21
	v_fmac_f32_e32 v37, v5, v5
	v_add_f32_e32 v35, v37, v35
	v_mul_f32_e32 v37, v22, v22
	v_fmac_f32_e32 v37, v6, v6
	v_add_f32_e32 v35, v37, v35
	v_mul_f32_e32 v37, v23, v23
	v_fmac_f32_e32 v37, v7, v7
	v_pk_mul_f32 v[38:39], v[24:25], v[24:25]
	v_add_f32_e32 v35, v37, v35
	v_pk_fma_f32 v[38:39], v[8:9], v[8:9], v[38:39]
	v_pk_mul_f32 v[40:41], v[26:27], v[26:27]
	v_add_f32_e32 v35, v38, v35
	v_pk_fma_f32 v[40:41], v[10:11], v[10:11], v[40:41]
	v_add_f32_e32 v35, v39, v35
	v_pk_mul_f32 v[42:43], v[28:29], v[28:29]
	v_add_f32_e32 v35, v40, v35
	v_pk_fma_f32 v[42:43], v[12:13], v[12:13], v[42:43]
	v_add_f32_e32 v35, v41, v35
	v_pk_mul_f32 v[44:45], v[30:31], v[30:31]
	v_add_f32_e32 v35, v42, v35
	v_pk_fma_f32 v[44:45], v[14:15], v[14:15], v[44:45]
	v_add_f32_e32 v35, v43, v35
	v_and_b32_e32 v38, 64, v132
	v_pk_mul_f32 v[46:47], v[32:33], v[32:33]
	v_add_f32_e32 v35, v44, v35
	v_xor_b32_e32 v37, 32, v132
	v_add_u32_e32 v38, 64, v38
	v_pk_fma_f32 v[46:47], v[16:17], v[16:17], v[46:47]
	v_add_f32_e32 v35, v45, v35
	v_cmp_lt_i32_e64 s[10:11], v37, v38
	v_add_f32_e32 v35, v46, v35
	v_add_f32_e32 v35, v47, v35
	v_cndmask_b32_e64 v37, v132, v37, s[10:11]
	v_lshlrev_b32_e32 v37, 2, v37
	ds_bpermute_b32 v42, v37, v35
	v_permlane32_swap_b32_e32 v2, v18
	v_permlane32_swap_b32_e32 v3, v19
	v_permlane32_swap_b32_e32 v4, v20
	v_permlane32_swap_b32_e32 v5, v21
	v_permlane32_swap_b32_e32 v6, v22
	v_permlane32_swap_b32_e32 v7, v23
	v_permlane32_swap_b32_e32 v8, v24
	v_permlane32_swap_b32_e32 v9, v25
	v_permlane32_swap_b32_e32 v10, v26
	v_permlane32_swap_b32_e32 v11, v27
	v_permlane32_swap_b32_e32 v12, v28
	v_permlane32_swap_b32_e32 v13, v29
	v_permlane32_swap_b32_e32 v14, v30
	v_permlane32_swap_b32_e32 v15, v31
	v_permlane32_swap_b32_e32 v16, v32
	v_permlane32_swap_b32_e32 v17, v33
	v_ashrrev_i32_e32 v37, 31, v36
	s_and_saveexec_b64 s[10:11], s[6:7]
	s_xor_b64 s[6:7], exec, s[10:11]
	v_lshlrev_b64 v[36:37], 10, v[36:37]
	v_lshl_add_u64 v[40:41], v[110:111], 0, v[36:37]
	s_or_saveexec_b64 s[6:7], s[6:7]
	s_mov_b64 s[10:11], 0
	s_xor_b64 exec, exec, s[6:7]
	v_lshl_add_u64 v[36:37], v[106:107], 0, v[36:37]
	v_lshlrev_b64 v[36:37], 7, v[36:37]
	v_lshl_add_u64 v[40:41], s[22:23], 0, v[36:37]
	s_and_b64 s[10:11], s[8:9], exec
	s_or_b64 exec, exec, s[6:7]
	v_readlane_b32 s76, v245, 16
	v_readlane_b32 s77, v245, 17
	v_readlane_b32 s78, v245, 18
	v_readlane_b32 s79, v245, 19
	v_readlane_b32 s80, v245, 20
	v_readlane_b32 s81, v245, 21
	v_readlane_b32 s82, v245, 22
	v_readlane_b32 s83, v245, 23
	v_readlane_b32 s84, v245, 24
	v_readlane_b32 s85, v245, 25
	v_readlane_b32 s86, v245, 26
	v_readlane_b32 s87, v245, 27
	v_readlane_b32 s88, v245, 28
	v_readlane_b32 s89, v245, 29
	v_readlane_b32 s90, v245, 30
	v_readlane_b32 s91, v245, 31
	s_mov_b64 s[76:77], s[80:81]
	s_mov_b64 s[78:79], s[82:83]
	s_mov_b64 s[80:81], s[84:85]
	s_mov_b64 s[82:83], s[86:87]
	s_mov_b64 s[84:85], s[88:89]
	s_mov_b64 s[86:87], s[90:91]
	v_mov_b32_e32 v36, s85
	v_mov_b32_e32 v37, s87
	v_cndmask_b32_e64 v37, v36, v37, s[4:5]
	v_mov_b32_e32 v36, s84
	v_mov_b32_e32 v38, s86
	v_cndmask_b32_e64 v36, v36, v38, s[4:5]
	v_lshlrev_b32_e32 v98, 2, v100
	v_lshl_add_u64 v[38:39], v[36:37], 0, v[98:99]
	s_waitcnt lgkmcnt(0)
	v_add_f32_e32 v35, v35, v42
	v_fmamk_f32 v35, v35, 0x3c800000, v124
	v_mul_f32_e32 v36, 0x4b800000, v35
	v_cmp_gt_f32_e64 s[6:7], s58, v35
	s_nop 1
	v_cndmask_b32_e64 v35, v35, v36, s[6:7]
	v_rsq_f32_e32 v35, v35
	s_nop 0
	v_mul_f32_e32 v36, 0x45800000, v35
	v_cndmask_b32_e64 v36, v35, v36, s[6:7]
	v_pk_mul_f32 v[2:3], v[36:37], v[2:3] op_sel_hi:[0,1]
	v_pk_mul_f32 v[4:5], v[36:37], v[4:5] op_sel_hi:[0,1]
	v_pk_mul_f32 v[42:43], v[36:37], v[18:19] op_sel_hi:[0,1]
	v_pk_mul_f32 v[52:53], v[36:37], v[20:21] op_sel_hi:[0,1]
	v_add_u32_e32 v35, v158, v157
	v_pk_mul_f32 v[18:19], v[2:3], v[246:247]
	v_pk_mul_f32 v[20:21], v[4:5], v[248:249]
	v_pk_mul_f32 v[2:3], v[42:43], v[214:215]
	v_pk_mul_f32 v[4:5], v[52:53], v[216:217]
	s_and_saveexec_b64 s[6:7], s[10:11]
	s_cbranch_execz .LBB0_355
	ds_write_b128 v35, v[18:21]
	ds_write_b128 v35, v[2:5] offset:16
.LBB0_355:
	s_or_b64 exec, exec, s[6:7]
	v_pk_mul_f32 v[18:19], v[104:105], v[18:19] op_sel_hi:[0,1]
	v_pk_mul_f32 v[20:21], v[104:105], v[20:21] op_sel_hi:[0,1]
	v_pk_mul_f32 v[2:3], v[104:105], v[2:3] op_sel_hi:[0,1]
	v_lshlrev_b32_e32 v98, 1, v100
	v_cvt_pk_bf16_f32 v18, v18, v19
	v_cvt_pk_bf16_f32 v19, v20, v21
	v_cvt_pk_bf16_f32 v20, v2, v3
	v_pk_mul_f32 v[2:3], v[104:105], v[4:5] op_sel_hi:[0,1]
	v_lshl_add_u64 v[40:41], v[40:41], 0, v[98:99]
	v_cvt_pk_bf16_f32 v21, v2, v3
	ds_write_b128 v202, v[18:21]
	s_nop 1
	v_mov_b32_e32 v37, v36
	v_pk_mul_f32 v[6:7], v[36:37], v[6:7]
	v_pk_mul_f32 v[8:9], v[36:37], v[8:9]
	v_pk_mul_f32 v[22:23], v[36:37], v[22:23]
	v_pk_mul_f32 v[24:25], v[36:37], v[24:25]
	v_pk_mul_f32 v[6:7], v[6:7], v[218:219]
	v_pk_mul_f32 v[8:9], v[8:9], v[220:221]
	v_pk_mul_f32 v[2:3], v[22:23], v[222:223]
	v_pk_mul_f32 v[4:5], v[24:25], v[224:225]
	s_and_saveexec_b64 s[6:7], s[10:11]
	s_cbranch_execz .LBB0_357
	ds_write_b128 v35, v[6:9] offset:32
	ds_write_b128 v35, v[2:5] offset:48
.LBB0_357:
	s_or_b64 exec, exec, s[6:7]
	v_mov_b32_e32 v105, v104
	v_pk_mul_f32 v[6:7], v[104:105], v[6:7]
	v_pk_mul_f32 v[8:9], v[104:105], v[8:9]
	v_pk_mul_f32 v[2:3], v[104:105], v[2:3]
	v_cvt_pk_bf16_f32 v6, v6, v7
	v_cvt_pk_bf16_f32 v7, v8, v9
	v_cvt_pk_bf16_f32 v8, v2, v3
	v_pk_mul_f32 v[2:3], v[104:105], v[4:5]
	s_nop 0
	v_cvt_pk_bf16_f32 v9, v2, v3
	ds_write_b128 v202, v[6:9] offset:16
	s_nop 1
	v_pk_mul_f32 v[6:7], v[36:37], v[10:11]
	v_pk_mul_f32 v[8:9], v[36:37], v[12:13]
	v_pk_mul_f32 v[10:11], v[36:37], v[26:27]
	v_pk_mul_f32 v[12:13], v[36:37], v[28:29]
	v_pk_mul_f32 v[6:7], v[6:7], v[226:227]
	v_pk_mul_f32 v[8:9], v[8:9], v[228:229]
	v_pk_mul_f32 v[2:3], v[10:11], v[230:231]
	v_pk_mul_f32 v[4:5], v[12:13], v[232:233]
	s_and_saveexec_b64 s[6:7], s[10:11]
	s_cbranch_execz .LBB0_359
	ds_write_b128 v35, v[6:9] offset:64
	ds_write_b128 v35, v[2:5] offset:80
.LBB0_359:
	s_or_b64 exec, exec, s[6:7]
	v_pk_mul_f32 v[6:7], v[104:105], v[6:7]
	v_pk_mul_f32 v[8:9], v[104:105], v[8:9]
	v_pk_mul_f32 v[2:3], v[104:105], v[2:3]
	v_cvt_pk_bf16_f32 v6, v6, v7
	v_cvt_pk_bf16_f32 v7, v8, v9
	v_cvt_pk_bf16_f32 v8, v2, v3
	v_pk_mul_f32 v[2:3], v[104:105], v[4:5]
	s_nop 0
	v_cvt_pk_bf16_f32 v9, v2, v3
	ds_write_b128 v202, v[6:9] offset:32
	s_nop 1
	v_pk_mul_f32 v[6:7], v[36:37], v[14:15]
	v_pk_mul_f32 v[8:9], v[36:37], v[16:17]
	v_pk_mul_f32 v[14:15], v[36:37], v[30:31]
	v_pk_mul_f32 v[16:17], v[36:37], v[32:33]
	v_pk_mul_f32 v[6:7], v[6:7], v[234:235]
	v_pk_mul_f32 v[8:9], v[8:9], v[236:237]
	v_pk_mul_f32 v[2:3], v[14:15], v[238:239]
	v_pk_mul_f32 v[4:5], v[16:17], v[240:241]
	s_and_saveexec_b64 s[6:7], s[10:11]
	s_cbranch_execz .LBB0_361
	ds_write_b128 v35, v[6:9] offset:96
	ds_write_b128 v35, v[2:5] offset:112
